# v6 stack plus attention-queue ticket prefetch (next pop's atomic issued ahead of the unit's epilogue stores)
# speedup vs baseline: 1.0107x; 1.0008x over previous
.LBB0_151:
	v_readlane_b32 s0, v252, 0
	s_mov_b32 s78, s0
	v_readlane_b32 s0, v254, 5
	s_ashr_i32 s2, s0, 2
	s_and_b32 s3, s0, 3
	s_lshl_b32 s0, s2, 6
	s_ashr_i32 s1, s0, 31
	v_writelane_b32 v254, s0, 8
	s_lshl_b32 s79, s2, 5
	s_lshl_b32 s4, s2, 9
	v_writelane_b32 v254, s1, 9
	s_mov_b32 s0, s2
	v_writelane_b32 v254, s0, 10
	s_mov_b64 s[10:11], -1
	s_mov_b64 s[12:13], 0
	v_writelane_b32 v254, s1, 11
	s_lshl_b32 s0, s2, 4
	v_writelane_b32 v254, s0, 12
	v_writelane_b32 v254, s73, 13
	v_writelane_b32 v254, s80, 14
	s_cmp_lt_i32 s3, 2
	s_mov_b64 s[8:9], 0
	v_writelane_b32 v254, s81, 15
	s_cbranch_scc1 .LBB0_359
	s_cmp_eq_u32 s3, 2
	s_mov_b64 s[8:9], -1
	s_cbranch_scc0 .LBB0_358
	v_writelane_b32 v254, s3, 16
	v_cmp_eq_u32_e64 s[42:43], 0, v218
	v_readlane_b32 s0, v254, 8
	v_readlane_b32 s1, v254, 9
	s_lshl_b64 s[2:3], s[0:1], 2
	v_readlane_b32 s0, v252, 13
	s_add_u32 s2, s0, s2
	v_readlane_b32 s0, v252, 14
	s_addc_u32 s3, s0, s3
	v_writelane_b32 v254, s2, 17
	s_nop 1
	v_writelane_b32 v254, s3, 18
	s_nop 0
	v_readlane_b32 s0, v254, 10
	v_readlane_b32 s1, v254, 11
	s_lshl_b32 s0, s0, 3
	s_ashr_i32 s1, s0, 31
	v_writelane_b32 v254, s0, 19
	s_nop 1
	v_writelane_b32 v254, s1, 20
	s_add_u32 s0, s88, 0x4800000
	v_writelane_b32 v254, s0, 21
	s_addc_u32 s0, s89, 0
	v_writelane_b32 v254, s0, 23
	s_add_u32 s0, s88, 0x4e00000
	v_writelane_b32 v254, s0, 24
	s_addc_u32 s0, s89, 0
	v_writelane_b32 v254, s0, 25
	s_add_u32 s0, s88, 0x5000000
	v_writelane_b32 v254, s0, 26
	s_addc_u32 s0, s89, 0
	v_writelane_b32 v254, s0, 27
	s_add_u32 s0, s88, 0x6900000
	v_writelane_b32 v254, s0, 28
	s_addc_u32 s0, s89, 0
	v_writelane_b32 v254, s0, 30
	s_add_u32 s0, s88, 0x8200000
	v_writelane_b32 v254, s0, 31
	s_addc_u32 s0, s89, 0
	v_writelane_b32 v254, s0, 33
	s_add_u32 s0, s88, 0x8e00000
	v_writelane_b32 v254, s0, 34
	s_addc_u32 s0, s89, 0
	v_writelane_b32 v254, s0, 36
	s_add_u32 s0, s88, 0x5800000
	v_writelane_b32 v254, s0, 37
	s_addc_u32 s0, s89, 0
	v_writelane_b32 v254, s0, 39
	s_add_u32 s0, s88, 0xa00000
	v_writelane_b32 v254, s0, 41
	s_addc_u32 s0, s89, 0
	v_writelane_b32 v254, s0, 43
	s_add_u32 s0, s88, 0x400000
	v_writelane_b32 v254, s0, 44
	s_addc_u32 s0, s89, 0
	v_writelane_b32 v254, s0, 46
	s_add_u32 s0, s88, 0x600000
	v_writelane_b32 v254, s0, 48
	s_addc_u32 s0, s89, 0
	v_writelane_b32 v254, s0, 50
	s_add_u32 s0, s88, 0x3c00000
	v_writelane_b32 v254, s0, 52
	s_addc_u32 s0, s89, 0
	v_writelane_b32 v254, s0, 53
	s_add_u32 s0, s88, 0x4000000
	v_writelane_b32 v254, s0, 54
	s_addc_u32 s0, s89, 0
	v_writelane_b32 v254, s0, 56
	s_add_u32 s0, s88, 0x4400000
	v_writelane_b32 v254, s0, 57
	s_addc_u32 s0, s89, 0
	s_cmp_eq_u32 s73, 0
	v_writelane_b32 v254, s0, 58
	s_cselect_b64 s[12:13], -1, 0
	s_add_u32 s0, s88, 0x8000
	v_writelane_b32 v254, s0, 59
	s_addc_u32 s0, s89, 0
	s_add_u32 s14, s88, 0x4200
	v_writelane_b32 v254, s0, 60
	s_addc_u32 s15, s89, 0
	s_and_b32 s0, s73, 3
	s_ashr_i32 s2, s73, 2
	s_lshl_b32 s1, s2, 5
	s_lshl_b32 s2, s2, 12
	s_lshl_b32 s3, s0, 10
	s_or_b32 s80, s2, s3
	s_lshl_b32 s51, s73, 5
	s_lshl_b32 s5, s0, 12
	s_addk_i32 s80, 0x3000
	s_lshl_b32 s16, s73, 10
	s_lshl_b32 s10, s73, 3
	s_and_b32 s6, s51, 32
	s_add_i32 s7, s5, s1
	s_add_i32 s17, s16, 0
	s_add_i32 s38, s80, 0
	s_bfe_u32 s2, s73, 0x10001
	s_cmp_eq_u32 s2, 0
	s_cselect_b64 s[8:9], -1, 0
	v_writelane_b32 v254, s8, 61
	s_add_u32 s5, s88, 0xa200
	s_mov_b32 s81, s1
	v_writelane_b32 v254, s9, 62
	v_writelane_b32 v254, s5, 63
	s_addc_u32 s5, s89, 0
	s_cmp_lt_i32 s73, 4
	v_writelane_b32 v255, s5, 0
	s_cselect_b64 s[8:9], -1, 0
	v_writelane_b32 v255, s8, 2
	s_lshl_b32 s2, s2, 16
	v_readlane_b32 s5, v252, 15
	v_writelane_b32 v255, s9, 3
	s_add_u32 s2, s5, s2
	v_readlane_b32 s5, v252, 16
	s_addc_u32 s5, s5, 0
	v_writelane_b32 v255, s6, 4
	s_lshl_b32 s6, s6, 8
	s_add_u32 s2, s2, s6
	v_writelane_b32 v255, s2, 6
	s_addc_u32 s2, s5, 0
	v_writelane_b32 v255, s2, 7
	s_add_u32 s2, s88, 0x300000
	v_writelane_b32 v255, s2, 8
	s_addc_u32 s2, s89, 0
	s_add_u32 s39, s88, 0x1800
	s_addc_u32 s8, s89, 0
	v_writelane_b32 v255, s2, 9
	s_add_u32 s2, s88, 0x9000
	v_writelane_b32 v255, s2, 10
	s_addc_u32 s2, s89, 0
	v_writelane_b32 v255, s2, 11
	s_lshl_b32 s2, s73, 9
	s_add_i32 s2, s2, 0
	s_add_i32 s2, s2, 0x21800
	v_writelane_b32 v255, s2, 12
	s_add_u32 s18, s88, 0x5900000
	s_mul_i32 s2, s73, 0x2200
	s_addc_u32 s19, s89, 0
	s_add_i32 s9, s2, 0
	s_add_u32 s26, s88, 0x7200000
	s_addc_u32 s27, s89, 0
	s_lshl_b32 s2, s0, 11
	v_writelane_b32 v255, s7, 13
	s_sub_i32 s5, s7, s2
	v_writelane_b32 v255, s5, 14
	s_lshl_b32 s5, s73, 7
	s_add_i32 s6, s5, 0
	s_add_i32 s6, s6, 0x22800
	s_add_u32 s5, s88, 0x9800
	v_writelane_b32 v255, s5, 15
	s_addc_u32 s5, s89, 0
	v_writelane_b32 v255, s5, 16
	s_add_u32 s5, s88, 0x8800
	v_writelane_b32 v255, s5, 17
	s_addc_u32 s5, s89, 0
	v_writelane_b32 v255, s5, 18
	s_lshl_b32 s5, s0, 4
	s_add_i32 s3, s3, 0
	v_writelane_b32 v255, s5, 19
	s_add_i32 s7, s3, 0x2000
	v_writelane_b32 v255, s3, 20
	s_add_u32 s3, s88, 0x4410000
	v_writelane_b32 v255, s3, 22
	s_addc_u32 s3, s89, 0
	v_writelane_b32 v255, s3, 23
	s_add_u32 s3, s88, 0x4010000
	v_writelane_b32 v255, s3, 24
	s_addc_u32 s3, s89, 0
	v_writelane_b32 v255, s3, 25
	s_lshl_b32 s3, s73, 11
	v_writelane_b32 v255, s3, 26
	s_add_i32 s2, s2, s1
	v_writelane_b32 v255, s2, 27
	s_lshl_b32 s2, s0, 9
	s_mulk_i32 s0, 0x3000
	v_writelane_b32 v255, s2, 29
	s_add_i32 s0, s0, s1
	v_writelane_b32 v255, s0, 30
	v_readlane_b32 s100, v254, 17
	v_readlane_b32 s101, v254, 18
	s_nop 3
	v_mov_b32_e32 v174, s100
	v_mov_b32_e32 v175, s101
	v_cmp_eq_u32_e64 s[100:101], 0, v218
	s_nop 3
	s_mov_b64 exec, s[100:101]
	global_atomic_add v221, v[174:175], v181, off sc0
	s_mov_b64 exec, -1
	s_branch .LBB0_156

.LBB0_156:
	s_waitcnt lgkmcnt(0)
	s_barrier
	s_and_saveexec_b64 s[28:29], s[42:43]
	s_cbranch_execz .LBB0_160
	s_mov_b64 s[40:41], exec
	v_readlane_b32 s0, v253, 61
	s_waitcnt vmcnt(0)
	s_nop 1
	v_mov_b32_e32 v1, s0
	ds_write_b32 v1, v221

.LBB0_205:
	v_cmp_eq_u32_e64 s[100:101], 0, v218
	s_nop 3
	s_mov_b64 exec, s[100:101]
	global_atomic_add v221, v[174:175], v181, off sc0
	s_mov_b64 exec, -1
	v_readlane_b32 s0, v254, 10
	s_mul_i32 s0, s0, 63
	s_add_i32 s2, s2, s0
	s_ashr_i32 s3, s2, 31
	s_lshl_b64 s[2:3], s[2:3], 2
	v_readlane_b32 s0, v254, 63
	s_add_u32 s64, s0, s2
	v_readlane_b32 s0, v255, 0
	v_readlane_b32 s1, v254, 11
	s_addc_u32 s65, s0, s3
	s_barrier
	s_mov_b64 s[40:41], s[42:43]
	s_movk_i32 s0, 0xfe40
	s_branch .LBB0_265

.LBB0_264:
	s_or_b64 exec, exec, s[56:57]
	s_lshl_b64 s[36:37], s[52:53], 2
	s_add_u32 s64, s39, s36
	s_addc_u32 s65, s8, s37
	v_ashrrev_i32_e32 v56, 3, v80
	s_add_i32 s0, s40, s51
	s_lshl_b32 s60, s2, 1
	v_lshlrev_b32_e32 v33, 3, v80
	v_add_u32_e32 v32, s0, v56
	s_add_u32 s2, s18, s60
	v_and_b32_e32 v57, 56, v33
	s_addc_u32 s3, s19, 0
	v_lshlrev_b32_e32 v80, 1, v57
	v_ashrrev_i32_e32 v33, 31, v32
	v_add_u32_e32 v38, 8, v32
	v_lshl_add_u64 v[34:35], s[2:3], 0, v[80:81]
	v_lshlrev_b64 v[52:53], 11, v[32:33]
	v_ashrrev_i32_e32 v39, 31, v38
	v_lshl_add_u64 v[36:37], v[34:35], 0, v[52:53]
	v_lshlrev_b64 v[54:55], 11, v[38:39]
	s_waitcnt lgkmcnt(0)
	s_barrier
	v_lshl_add_u64 v[38:39], v[34:35], 0, v[54:55]
	global_load_dwordx4 v[40:43], v[36:37], off
	global_load_dwordx4 v[44:47], v[38:39], off
	v_add_u32_e32 v36, 16, v32
	v_add_u32_e32 v32, 24, v32
	v_ashrrev_i32_e32 v37, 31, v36
	v_ashrrev_i32_e32 v33, 31, v32
	s_movk_i32 s0, 0x440
	v_lshlrev_b64 v[38:39], 11, v[36:37]
	v_lshlrev_b64 v[36:37], 11, v[32:33]
	v_lshlrev_b32_e32 v58, 2, v114
	v_mul_lo_u32 v59, v136, s0
	v_lshl_add_u64 v[48:49], v[34:35], 0, v[38:39]
	v_lshl_add_u64 v[32:33], v[34:35], 0, v[36:37]
	v_add3_u32 v58, s9, v58, v59
	global_load_dwordx4 v[48:51], v[48:49], off
	s_nop 0
	global_load_dwordx4 v[32:35], v[32:33], off
	ds_write2_b32 v58, v16, v0 offset1:32
	ds_write2_b32 v58, v17, v1 offset0:68 offset1:100
	ds_write2_b32 v58, v18, v2 offset0:136 offset1:168
	ds_write2_b32 v58, v19, v3 offset0:204 offset1:236
	v_add_u32_e32 v0, 0x800, v58
	ds_write2_b32 v0, v20, v4 offset0:32 offset1:64
	ds_write2_b32 v0, v21, v5 offset0:100 offset1:132
	ds_write2_b32 v0, v22, v6 offset0:168 offset1:200
	v_add_u32_e32 v0, 0xa00, v58
	ds_write2_b32 v0, v23, v7 offset0:108 offset1:140
	v_add_u32_e32 v0, 0x1000, v58
	ds_write2_b32 v0, v24, v8 offset0:64 offset1:96
	ds_write2_b32 v0, v25, v9 offset0:132 offset1:164
	ds_write2_b32 v0, v26, v10 offset0:200 offset1:232
	v_add_u32_e32 v0, 0x1400, v58
	ds_write2_b32 v0, v27, v11 offset0:12 offset1:44
	v_add_u32_e32 v0, 0x1800, v58
	ds_write2_b32 v0, v28, v12 offset0:96 offset1:128
	ds_write2_b32 v0, v29, v13 offset0:164 offset1:196
	v_add_u32_e32 v0, 0x1a00, v58
	ds_write2_b32 v0, v30, v14 offset0:104 offset1:136
	v_add_u32_e32 v0, 0x1c00, v58
	ds_write2_b32 v0, v31, v15 offset0:44 offset1:76
	v_lshlrev_b32_e32 v0, 2, v57
	v_mul_lo_u32 v1, v56, s77
	v_add3_u32 v16, s9, v0, v1
	s_waitcnt lgkmcnt(0)
	ds_read_b128 v[0:3], v16
	ds_read_b128 v[4:7], v16 offset:16
	s_mov_b64 s[40:41], s[42:43]
	s_waitcnt lgkmcnt(0)
	v_pk_mul_f32 v[8:9], v[2:3], v[2:3]
	v_pk_mul_f32 v[10:11], v[0:1], v[0:1]
	s_nop 0
	v_pk_mov_b32 v[12:13], v[10:11], v[8:9] op_sel:[1,0]
	v_mov_b32_e32 v11, v9
	v_pk_add_f32 v[8:9], v[12:13], v[10:11]
	v_pk_mul_f32 v[10:11], v[6:7], v[6:7]
	v_pk_mul_f32 v[12:13], v[4:5], v[4:5]
	v_mov_b32_e32 v14, v10
	v_mov_b32_e32 v15, v12
	v_mov_b32_e32 v12, v11
	v_pk_add_f32 v[10:11], v[14:15], v[12:13]
	v_add_f32_e32 v8, v8, v9
	v_add_f32_e32 v8, v8, v11
	v_add_f32_e32 v8, v10, v8
	s_nop 1
	v_add_f32_dpp v8, v8, v8 quad_perm:[1,0,3,2] row_mask:0xf bank_mask:0xf
	s_nop 1
	v_add_f32_dpp v8, v8, v8 quad_perm:[2,3,0,1] row_mask:0xf bank_mask:0xf
	s_nop 1
	v_add_f32_dpp v8, v8, v8 row_half_mirror row_mask:0xf bank_mask:0xf
	v_fmamk_f32 v8, v8, 0x3c800000, v180
	v_mul_f32_e32 v9, 0x4b800000, v8
	v_cmp_gt_f32_e32 vcc, s1, v8
	s_waitcnt vmcnt(0)
	v_lshlrev_b32_e32 v10, 16, v40
	v_cndmask_b32_e32 v8, v8, v9, vcc
	v_rsq_f32_e32 v8, v8
	v_and_b32_e32 v11, 0xffff0000, v40
	v_mul_f32_e32 v9, 0x45800000, v8
	v_cndmask_b32_e32 v8, v8, v9, vcc
	v_pk_mul_f32 v[0:1], v[0:1], v[8:9] op_sel_hi:[1,0]
	v_pk_mul_f32 v[2:3], v[2:3], v[8:9] op_sel_hi:[1,0]
	v_pk_mul_f32 v[0:1], v[0:1], v[10:11]
	v_lshlrev_b32_e32 v10, 16, v41
	v_and_b32_e32 v11, 0xffff0000, v41
	v_pk_mul_f32 v[2:3], v[2:3], v[10:11]
	v_cvt_pk_bf16_f32 v0, v0, v1
	v_cvt_pk_bf16_f32 v1, v2, v3
	v_pk_mul_f32 v[2:3], v[4:5], v[8:9] op_sel_hi:[1,0]
	v_lshlrev_b32_e32 v4, 16, v42
	v_and_b32_e32 v5, 0xffff0000, v42
	v_pk_mul_f32 v[2:3], v[2:3], v[4:5]
	v_pk_mul_f32 v[4:5], v[6:7], v[8:9] op_sel_hi:[1,0]
	v_lshlrev_b32_e32 v6, 16, v43
	v_and_b32_e32 v7, 0xffff0000, v43
	v_pk_mul_f32 v[4:5], v[4:5], v[6:7]
	v_cvt_pk_bf16_f32 v2, v2, v3
	v_cvt_pk_bf16_f32 v3, v4, v5
	v_lshl_add_u64 v[4:5], s[26:27], 0, v[52:53]
	v_lshl_add_u64 v[4:5], v[4:5], 0, s[60:61]
	v_lshl_add_u64 v[4:5], v[4:5], 0, v[80:81]
	v_cmp_eq_u32_e64 s[100:101], 0, v218
	s_nop 3
	s_mov_b64 exec, s[100:101]
	global_atomic_add v221, v[174:175], v181, off sc0
	s_mov_b64 exec, -1
	global_store_dwordx4 v[4:5], v[0:3], off sc1
	s_nop 1
	ds_read_b128 v[0:3], v16 offset:2176
	ds_read_b128 v[4:7], v16 offset:2192
	s_waitcnt lgkmcnt(1)
	v_pk_mul_f32 v[8:9], v[2:3], v[2:3]
	v_pk_mul_f32 v[10:11], v[0:1], v[0:1]
	s_nop 0
	v_pk_mov_b32 v[12:13], v[10:11], v[8:9] op_sel:[1,0]
	v_mov_b32_e32 v11, v9
	v_pk_add_f32 v[8:9], v[12:13], v[10:11]
	s_waitcnt lgkmcnt(0)
	v_pk_mul_f32 v[10:11], v[6:7], v[6:7]
	v_pk_mul_f32 v[12:13], v[4:5], v[4:5]
	v_mov_b32_e32 v14, v10
	v_mov_b32_e32 v15, v12
	v_mov_b32_e32 v12, v11
	v_pk_add_f32 v[10:11], v[14:15], v[12:13]
	v_add_f32_e32 v8, v8, v9
	v_add_f32_e32 v8, v8, v11
	v_add_f32_e32 v8, v10, v8
	v_lshlrev_b32_e32 v10, 16, v44
	v_and_b32_e32 v11, 0xffff0000, v44
	s_nop 1
	v_add_f32_dpp v8, v8, v8 quad_perm:[1,0,3,2] row_mask:0xf bank_mask:0xf
	s_nop 1
	v_add_f32_dpp v8, v8, v8 quad_perm:[2,3,0,1] row_mask:0xf bank_mask:0xf
	s_nop 1
	v_add_f32_dpp v8, v8, v8 row_half_mirror row_mask:0xf bank_mask:0xf
	v_fmamk_f32 v8, v8, 0x3c800000, v180
	v_mul_f32_e32 v9, 0x4b800000, v8
	v_cmp_gt_f32_e32 vcc, s1, v8
	s_nop 1
	v_cndmask_b32_e32 v8, v8, v9, vcc
	v_rsq_f32_e32 v8, v8
	s_nop 0
	v_mul_f32_e32 v9, 0x45800000, v8
	v_cndmask_b32_e32 v8, v8, v9, vcc
	v_pk_mul_f32 v[0:1], v[0:1], v[8:9] op_sel_hi:[1,0]
	v_pk_mul_f32 v[2:3], v[2:3], v[8:9] op_sel_hi:[1,0]
	v_pk_mul_f32 v[0:1], v[0:1], v[10:11]
	v_lshlrev_b32_e32 v10, 16, v45
	v_and_b32_e32 v11, 0xffff0000, v45
	v_pk_mul_f32 v[2:3], v[2:3], v[10:11]
	v_cvt_pk_bf16_f32 v0, v0, v1
	v_cvt_pk_bf16_f32 v1, v2, v3
	v_pk_mul_f32 v[2:3], v[4:5], v[8:9] op_sel_hi:[1,0]
	v_lshlrev_b32_e32 v4, 16, v46
	v_and_b32_e32 v5, 0xffff0000, v46
	v_pk_mul_f32 v[2:3], v[2:3], v[4:5]
	v_pk_mul_f32 v[4:5], v[6:7], v[8:9] op_sel_hi:[1,0]
	v_lshlrev_b32_e32 v6, 16, v47
	v_and_b32_e32 v7, 0xffff0000, v47
	v_pk_mul_f32 v[4:5], v[4:5], v[6:7]
	v_cvt_pk_bf16_f32 v2, v2, v3
	v_cvt_pk_bf16_f32 v3, v4, v5
	v_lshl_add_u64 v[4:5], s[26:27], 0, v[54:55]
	v_lshl_add_u64 v[4:5], v[4:5], 0, s[60:61]
	v_lshl_add_u64 v[4:5], v[4:5], 0, v[80:81]
	global_store_dwordx4 v[4:5], v[0:3], off sc1
	s_nop 1
	ds_read_b128 v[0:3], v16 offset:4352
	ds_read_b128 v[4:7], v16 offset:4368
	s_waitcnt lgkmcnt(1)
	v_pk_mul_f32 v[8:9], v[2:3], v[2:3]
	v_pk_mul_f32 v[10:11], v[0:1], v[0:1]
	s_nop 0
	v_pk_mov_b32 v[12:13], v[10:11], v[8:9] op_sel:[1,0]
	v_mov_b32_e32 v11, v9
	v_pk_add_f32 v[8:9], v[12:13], v[10:11]
	s_waitcnt lgkmcnt(0)
	v_pk_mul_f32 v[10:11], v[6:7], v[6:7]
	v_pk_mul_f32 v[12:13], v[4:5], v[4:5]
	v_mov_b32_e32 v14, v10
	v_mov_b32_e32 v15, v12
	v_mov_b32_e32 v12, v11
	v_pk_add_f32 v[10:11], v[14:15], v[12:13]
	v_add_f32_e32 v8, v8, v9
	v_add_f32_e32 v8, v8, v11
	v_add_f32_e32 v8, v10, v8
	v_lshlrev_b32_e32 v10, 16, v48
	v_and_b32_e32 v11, 0xffff0000, v48
	s_nop 1
	v_add_f32_dpp v8, v8, v8 quad_perm:[1,0,3,2] row_mask:0xf bank_mask:0xf
	s_nop 1
	v_add_f32_dpp v8, v8, v8 quad_perm:[2,3,0,1] row_mask:0xf bank_mask:0xf
	s_nop 1
	v_add_f32_dpp v8, v8, v8 row_half_mirror row_mask:0xf bank_mask:0xf
	v_fmamk_f32 v8, v8, 0x3c800000, v180
	v_mul_f32_e32 v9, 0x4b800000, v8
	v_cmp_gt_f32_e32 vcc, s1, v8
	s_nop 1
	v_cndmask_b32_e32 v8, v8, v9, vcc
	v_rsq_f32_e32 v8, v8
	s_nop 0
	v_mul_f32_e32 v9, 0x45800000, v8
	v_cndmask_b32_e32 v8, v8, v9, vcc
	v_pk_mul_f32 v[0:1], v[0:1], v[8:9] op_sel_hi:[1,0]
	v_pk_mul_f32 v[2:3], v[2:3], v[8:9] op_sel_hi:[1,0]
	v_pk_mul_f32 v[0:1], v[0:1], v[10:11]
	v_lshlrev_b32_e32 v10, 16, v49
	v_and_b32_e32 v11, 0xffff0000, v49
	v_pk_mul_f32 v[2:3], v[2:3], v[10:11]
	v_cvt_pk_bf16_f32 v0, v0, v1
	v_cvt_pk_bf16_f32 v1, v2, v3
	v_pk_mul_f32 v[2:3], v[4:5], v[8:9] op_sel_hi:[1,0]
	v_lshlrev_b32_e32 v4, 16, v50
	v_and_b32_e32 v5, 0xffff0000, v50
	v_pk_mul_f32 v[2:3], v[2:3], v[4:5]
	v_pk_mul_f32 v[4:5], v[6:7], v[8:9] op_sel_hi:[1,0]
	v_lshlrev_b32_e32 v6, 16, v51
	v_and_b32_e32 v7, 0xffff0000, v51
	v_pk_mul_f32 v[4:5], v[4:5], v[6:7]
	v_cvt_pk_bf16_f32 v2, v2, v3
	v_cvt_pk_bf16_f32 v3, v4, v5
	v_lshl_add_u64 v[4:5], s[26:27], 0, v[38:39]
	v_lshl_add_u64 v[4:5], v[4:5], 0, s[60:61]
	v_lshl_add_u64 v[4:5], v[4:5], 0, v[80:81]
	global_store_dwordx4 v[4:5], v[0:3], off sc1
	s_nop 1
	ds_read_b128 v[0:3], v16 offset:6528
	ds_read_b128 v[4:7], v16 offset:6544
	s_waitcnt lgkmcnt(1)
	v_pk_mul_f32 v[8:9], v[2:3], v[2:3]
	v_pk_mul_f32 v[10:11], v[0:1], v[0:1]
	s_nop 0
	v_pk_mov_b32 v[12:13], v[10:11], v[8:9] op_sel:[1,0]
	v_mov_b32_e32 v11, v9
	v_pk_add_f32 v[8:9], v[12:13], v[10:11]
	s_waitcnt lgkmcnt(0)
	v_pk_mul_f32 v[10:11], v[6:7], v[6:7]
	v_pk_mul_f32 v[12:13], v[4:5], v[4:5]
	v_mov_b32_e32 v14, v10
	v_mov_b32_e32 v15, v12
	v_mov_b32_e32 v12, v11
	v_pk_add_f32 v[10:11], v[14:15], v[12:13]
	v_add_f32_e32 v8, v8, v9
	v_add_f32_e32 v8, v8, v11
	v_add_f32_e32 v8, v10, v8
	v_lshlrev_b32_e32 v10, 16, v32
	v_and_b32_e32 v11, 0xffff0000, v32
	s_nop 1
	v_add_f32_dpp v8, v8, v8 quad_perm:[1,0,3,2] row_mask:0xf bank_mask:0xf
	s_nop 1
	v_add_f32_dpp v8, v8, v8 quad_perm:[2,3,0,1] row_mask:0xf bank_mask:0xf
	s_nop 1
	v_add_f32_dpp v8, v8, v8 row_half_mirror row_mask:0xf bank_mask:0xf
	v_fmamk_f32 v8, v8, 0x3c800000, v180
	v_mul_f32_e32 v9, 0x4b800000, v8
	v_cmp_gt_f32_e32 vcc, s1, v8
	s_nop 1
	v_cndmask_b32_e32 v8, v8, v9, vcc
	v_rsq_f32_e32 v8, v8
	s_nop 0
	v_mul_f32_e32 v9, 0x45800000, v8
	v_cndmask_b32_e32 v8, v8, v9, vcc
	v_pk_mul_f32 v[0:1], v[0:1], v[8:9] op_sel_hi:[1,0]
	v_pk_mul_f32 v[2:3], v[2:3], v[8:9] op_sel_hi:[1,0]
	v_pk_mul_f32 v[0:1], v[0:1], v[10:11]
	v_lshlrev_b32_e32 v10, 16, v33
	v_and_b32_e32 v11, 0xffff0000, v33
	v_pk_mul_f32 v[2:3], v[2:3], v[10:11]
	v_cvt_pk_bf16_f32 v0, v0, v1
	v_cvt_pk_bf16_f32 v1, v2, v3
	v_pk_mul_f32 v[2:3], v[4:5], v[8:9] op_sel_hi:[1,0]
	v_lshlrev_b32_e32 v4, 16, v34
	v_and_b32_e32 v5, 0xffff0000, v34
	v_pk_mul_f32 v[2:3], v[2:3], v[4:5]
	v_pk_mul_f32 v[4:5], v[6:7], v[8:9] op_sel_hi:[1,0]
	v_lshlrev_b32_e32 v6, 16, v35
	v_and_b32_e32 v7, 0xffff0000, v35
	v_pk_mul_f32 v[4:5], v[4:5], v[6:7]
	v_cvt_pk_bf16_f32 v2, v2, v3
	v_cvt_pk_bf16_f32 v3, v4, v5
	v_lshl_add_u64 v[4:5], s[26:27], 0, v[36:37]
	v_lshl_add_u64 v[4:5], v[4:5], 0, s[60:61]
	v_lshl_add_u64 v[4:5], v[4:5], 0, v[80:81]
	global_store_dwordx4 v[4:5], v[0:3], off sc1
	s_nop 1
	s_waitcnt vmcnt(0)
	s_barrier

.LBB0_315:
	s_or_b64 exec, exec, s[44:45]
	s_lshl_b64 s[36:37], s[40:41], 2
	s_add_u32 s64, s39, s36
	s_addc_u32 s65, s8, s37
	v_ashrrev_i32_e32 v56, 3, v80
	s_add_i32 s3, s3, s51
	v_lshlrev_b32_e32 v33, 3, v80
	s_waitcnt lgkmcnt(0)
	v_add_u32_e32 v32, s3, v56
	v_and_b32_e32 v57, 56, v33
	s_lshl_b64 s[2:3], s[62:63], 1
	v_lshlrev_b32_e32 v80, 1, v57
	v_ashrrev_i32_e32 v33, 31, v32
	s_add_u32 s2, s2, 0x200
	v_lshl_add_u64 v[34:35], s[18:19], 0, v[80:81]
	v_lshlrev_b64 v[54:55], 11, v[32:33]
	s_addc_u32 s3, s3, 0
	v_lshl_add_u64 v[36:37], v[34:35], 0, v[54:55]
	v_lshl_add_u64 v[36:37], v[36:37], 0, s[2:3]
	s_barrier
	global_load_dwordx4 v[44:47], v[36:37], off
	v_add_u32_e32 v36, 8, v32
	v_ashrrev_i32_e32 v37, 31, v36
	v_lshlrev_b64 v[52:53], 11, v[36:37]
	v_lshl_add_u64 v[36:37], v[34:35], 0, v[52:53]
	v_lshl_add_u64 v[36:37], v[36:37], 0, s[2:3]
	global_load_dwordx4 v[40:43], v[36:37], off
	v_add_u32_e32 v36, 16, v32
	v_ashrrev_i32_e32 v37, 31, v36
	v_lshlrev_b64 v[50:51], 11, v[36:37]
	v_lshl_add_u64 v[36:37], v[34:35], 0, v[50:51]
	v_lshl_add_u64 v[36:37], v[36:37], 0, s[2:3]
	global_load_dwordx4 v[36:39], v[36:37], off
	v_add_u32_e32 v32, 24, v32
	v_ashrrev_i32_e32 v33, 31, v32
	v_lshlrev_b64 v[48:49], 11, v[32:33]
	v_lshl_add_u64 v[32:33], v[34:35], 0, v[48:49]
	v_lshl_add_u64 v[32:33], v[32:33], 0, s[2:3]
	global_load_dwordx4 v[32:35], v[32:33], off
	s_movk_i32 s0, 0x440
	v_lshlrev_b32_e32 v58, 2, v121
	v_mul_lo_u32 v59, v120, s0
	v_add3_u32 v58, s9, v58, v59
	ds_write2_b32 v58, v0, v16 offset1:32
	ds_write2_b32 v58, v1, v17 offset0:68 offset1:100
	ds_write2_b32 v58, v2, v18 offset0:136 offset1:168
	ds_write2_b32 v58, v3, v19 offset0:204 offset1:236
	v_add_u32_e32 v0, 0x800, v58
	ds_write2_b32 v0, v4, v20 offset0:32 offset1:64
	ds_write2_b32 v0, v5, v21 offset0:100 offset1:132
	ds_write2_b32 v0, v6, v22 offset0:168 offset1:200
	v_add_u32_e32 v0, 0xa00, v58
	ds_write2_b32 v0, v7, v23 offset0:108 offset1:140
	v_add_u32_e32 v0, 0x1000, v58
	ds_write2_b32 v0, v8, v24 offset0:64 offset1:96
	ds_write2_b32 v0, v9, v25 offset0:132 offset1:164
	ds_write2_b32 v0, v10, v26 offset0:200 offset1:232
	v_add_u32_e32 v0, 0x1400, v58
	ds_write2_b32 v0, v11, v27 offset0:12 offset1:44
	v_add_u32_e32 v0, 0x1800, v58
	ds_write2_b32 v0, v12, v28 offset0:96 offset1:128
	ds_write2_b32 v0, v13, v29 offset0:164 offset1:196
	v_add_u32_e32 v0, 0x1a00, v58
	ds_write2_b32 v0, v14, v30 offset0:104 offset1:136
	v_add_u32_e32 v0, 0x1c00, v58
	ds_write2_b32 v0, v15, v31 offset0:44 offset1:76
	v_lshlrev_b32_e32 v0, 2, v57
	v_mul_lo_u32 v1, v56, s77
	v_add3_u32 v9, s9, v0, v1
	v_lshl_add_u32 v12, v56, 2, s6
	s_waitcnt lgkmcnt(0)
	ds_read_b128 v[4:7], v9
	ds_read_b128 v[0:3], v9 offset:16
	ds_read_b32 v8, v12
	s_mov_b64 s[0:1], 0x200
	s_mov_b64 s[40:41], s[42:43]
	s_waitcnt lgkmcnt(0)
	v_pk_mul_f32 v[4:5], v[4:5], v[8:9] op_sel_hi:[1,0]
	v_pk_mul_f32 v[6:7], v[6:7], v[8:9] op_sel_hi:[1,0]
	v_pk_mul_f32 v[0:1], v[0:1], v[8:9] op_sel_hi:[1,0]
	s_waitcnt vmcnt(0)
	v_lshlrev_b32_e32 v10, 16, v44
	v_and_b32_e32 v11, 0xffff0000, v44
	v_pk_mul_f32 v[4:5], v[4:5], v[10:11]
	v_lshlrev_b32_e32 v10, 16, v45
	v_and_b32_e32 v11, 0xffff0000, v45
	v_pk_mul_f32 v[6:7], v[6:7], v[10:11]
	v_cvt_pk_bf16_f32 v4, v4, v5
	v_cvt_pk_bf16_f32 v5, v6, v7
	v_lshlrev_b32_e32 v6, 16, v46
	v_and_b32_e32 v7, 0xffff0000, v46
	v_pk_mul_f32 v[0:1], v[0:1], v[6:7]
	v_lshlrev_b32_e32 v10, 16, v40
	v_cvt_pk_bf16_f32 v6, v0, v1
	v_pk_mul_f32 v[0:1], v[2:3], v[8:9] op_sel_hi:[1,0]
	v_lshlrev_b32_e32 v2, 16, v47
	v_and_b32_e32 v3, 0xffff0000, v47
	v_pk_mul_f32 v[0:1], v[0:1], v[2:3]
	v_and_b32_e32 v11, 0xffff0000, v40
	v_cvt_pk_bf16_f32 v7, v0, v1
	v_lshl_add_u64 v[0:1], s[26:27], 0, v[54:55]
	v_lshl_add_u64 v[0:1], v[0:1], 0, s[46:47]
	v_lshl_add_u64 v[0:1], v[0:1], 0, v[80:81]
	v_lshl_add_u64 v[0:1], v[0:1], 0, s[0:1]
	v_cmp_eq_u32_e64 s[100:101], 0, v218
	s_nop 3
	s_mov_b64 exec, s[100:101]
	global_atomic_add v221, v[174:175], v181, off sc0
	s_mov_b64 exec, -1
	global_store_dwordx4 v[0:1], v[4:7], off sc1
	s_nop 1
	ds_read_b128 v[0:3], v9 offset:2176
	ds_read_b128 v[4:7], v9 offset:2192
	ds_read_b32 v8, v12 offset:32
	s_waitcnt lgkmcnt(0)
	v_pk_mul_f32 v[0:1], v[0:1], v[8:9] op_sel_hi:[1,0]
	s_nop 0
	v_pk_mul_f32 v[0:1], v[0:1], v[10:11]
	v_pk_mul_f32 v[2:3], v[2:3], v[8:9] op_sel_hi:[1,0]
	v_lshlrev_b32_e32 v10, 16, v41
	v_and_b32_e32 v11, 0xffff0000, v41
	v_pk_mul_f32 v[2:3], v[2:3], v[10:11]
	v_cvt_pk_bf16_f32 v0, v0, v1
	v_cvt_pk_bf16_f32 v1, v2, v3
	v_pk_mul_f32 v[2:3], v[4:5], v[8:9] op_sel_hi:[1,0]
	v_lshlrev_b32_e32 v4, 16, v42
	v_and_b32_e32 v5, 0xffff0000, v42
	v_pk_mul_f32 v[2:3], v[2:3], v[4:5]
	v_pk_mul_f32 v[4:5], v[6:7], v[8:9] op_sel_hi:[1,0]
	v_lshlrev_b32_e32 v6, 16, v43
	v_and_b32_e32 v7, 0xffff0000, v43
	v_pk_mul_f32 v[4:5], v[4:5], v[6:7]
	v_cvt_pk_bf16_f32 v2, v2, v3
	v_cvt_pk_bf16_f32 v3, v4, v5
	v_lshl_add_u64 v[4:5], s[26:27], 0, v[52:53]
	v_lshl_add_u64 v[4:5], v[4:5], 0, s[46:47]
	v_lshl_add_u64 v[4:5], v[4:5], 0, v[80:81]
	v_lshl_add_u64 v[4:5], v[4:5], 0, s[0:1]
	global_store_dwordx4 v[4:5], v[0:3], off sc1
	s_nop 1
	ds_read_b128 v[0:3], v9 offset:4352
	ds_read_b128 v[4:7], v9 offset:4368
	ds_read_b32 v8, v12 offset:64
	v_lshlrev_b32_e32 v10, 16, v36
	v_and_b32_e32 v11, 0xffff0000, v36
	s_waitcnt lgkmcnt(0)
	v_pk_mul_f32 v[0:1], v[0:1], v[8:9] op_sel_hi:[1,0]
	s_nop 0
	v_pk_mul_f32 v[0:1], v[0:1], v[10:11]
	v_pk_mul_f32 v[2:3], v[2:3], v[8:9] op_sel_hi:[1,0]
	v_lshlrev_b32_e32 v10, 16, v37
	v_and_b32_e32 v11, 0xffff0000, v37
	v_pk_mul_f32 v[2:3], v[2:3], v[10:11]
	v_cvt_pk_bf16_f32 v0, v0, v1
	v_cvt_pk_bf16_f32 v1, v2, v3
	v_pk_mul_f32 v[2:3], v[4:5], v[8:9] op_sel_hi:[1,0]
	v_lshlrev_b32_e32 v4, 16, v38
	v_and_b32_e32 v5, 0xffff0000, v38
	v_pk_mul_f32 v[2:3], v[2:3], v[4:5]
	v_pk_mul_f32 v[4:5], v[6:7], v[8:9] op_sel_hi:[1,0]
	v_lshlrev_b32_e32 v6, 16, v39
	v_and_b32_e32 v7, 0xffff0000, v39
	v_pk_mul_f32 v[4:5], v[4:5], v[6:7]
	v_cvt_pk_bf16_f32 v2, v2, v3
	v_cvt_pk_bf16_f32 v3, v4, v5
	v_lshl_add_u64 v[4:5], s[26:27], 0, v[50:51]
	v_lshl_add_u64 v[4:5], v[4:5], 0, s[46:47]
	v_lshl_add_u64 v[4:5], v[4:5], 0, v[80:81]
	v_lshl_add_u64 v[4:5], v[4:5], 0, s[0:1]
	global_store_dwordx4 v[4:5], v[0:3], off sc1
	s_nop 1
	ds_read_b128 v[0:3], v9 offset:6528
	ds_read_b128 v[4:7], v9 offset:6544
	ds_read_b32 v8, v12 offset:96
	v_lshlrev_b32_e32 v10, 16, v32
	v_and_b32_e32 v11, 0xffff0000, v32
	s_waitcnt lgkmcnt(0)
	v_pk_mul_f32 v[0:1], v[0:1], v[8:9] op_sel_hi:[1,0]
	s_nop 0
	v_pk_mul_f32 v[0:1], v[0:1], v[10:11]
	v_pk_mul_f32 v[2:3], v[2:3], v[8:9] op_sel_hi:[1,0]
	v_lshlrev_b32_e32 v10, 16, v33
	v_and_b32_e32 v11, 0xffff0000, v33
	v_pk_mul_f32 v[2:3], v[2:3], v[10:11]
	v_cvt_pk_bf16_f32 v0, v0, v1
	v_cvt_pk_bf16_f32 v1, v2, v3
	v_pk_mul_f32 v[2:3], v[4:5], v[8:9] op_sel_hi:[1,0]
	v_lshlrev_b32_e32 v4, 16, v34
	v_and_b32_e32 v5, 0xffff0000, v34
	v_pk_mul_f32 v[2:3], v[2:3], v[4:5]
	v_pk_mul_f32 v[4:5], v[6:7], v[8:9] op_sel_hi:[1,0]
	v_lshlrev_b32_e32 v6, 16, v35
	v_and_b32_e32 v7, 0xffff0000, v35
	v_pk_mul_f32 v[4:5], v[4:5], v[6:7]
	v_cvt_pk_bf16_f32 v2, v2, v3
	v_cvt_pk_bf16_f32 v3, v4, v5
	v_lshl_add_u64 v[4:5], s[26:27], 0, v[48:49]
	v_lshl_add_u64 v[4:5], v[4:5], 0, s[46:47]
	v_lshl_add_u64 v[4:5], v[4:5], 0, v[80:81]
	v_lshl_add_u64 v[4:5], v[4:5], 0, s[0:1]
	global_store_dwordx4 v[4:5], v[0:3], off sc1
	s_nop 1
	s_waitcnt vmcnt(0)
	s_barrier

.LBB0_354:
	s_or_b64 exec, exec, s[28:29]
	s_ashr_i32 s0, s5, 8
	s_add_i32 s0, s0, s79
	s_lshl_b32 s28, s0, 2
	s_ashr_i32 s29, s28, 31
	s_lshl_b64 s[28:29], s[28:29], 2
	s_add_u32 s64, s39, s28
	s_addc_u32 s65, s8, s29
	s_lshl_b32 s0, s2, 6
	s_add_i32 s60, s0, 0x280
	v_ashrrev_i32_e32 v56, 3, v80
	s_add_i32 s5, s5, s51
	s_lshl_b64 s[28:29], s[60:61], 1
	v_lshlrev_b32_e32 v17, 3, v80
	s_waitcnt lgkmcnt(0)
	v_add_u32_e32 v16, s5, v56
	s_add_u32 s2, s18, s28
	v_and_b32_e32 v57, 56, v17
	s_addc_u32 s3, s19, s29
	v_lshlrev_b32_e32 v80, 1, v57
	v_ashrrev_i32_e32 v17, 31, v16
	v_lshl_add_u64 v[18:19], s[2:3], 0, v[80:81]
	v_lshlrev_b64 v[54:55], 11, v[16:17]
	v_lshl_add_u64 v[20:21], v[18:19], 0, v[54:55]
	s_barrier
	global_load_dwordx4 v[28:31], v[20:21], off
	v_add_u32_e32 v20, 8, v16
	v_ashrrev_i32_e32 v21, 31, v20
	v_lshlrev_b64 v[52:53], 11, v[20:21]
	v_lshl_add_u64 v[20:21], v[18:19], 0, v[52:53]
	global_load_dwordx4 v[24:27], v[20:21], off
	v_add_u32_e32 v20, 16, v16
	v_ashrrev_i32_e32 v21, 31, v20
	v_lshlrev_b64 v[50:51], 11, v[20:21]
	v_lshl_add_u64 v[20:21], v[18:19], 0, v[50:51]
	global_load_dwordx4 v[20:23], v[20:21], off
	v_add_u32_e32 v16, 24, v16
	v_ashrrev_i32_e32 v17, 31, v16
	v_lshlrev_b64 v[48:49], 11, v[16:17]
	v_lshl_add_u64 v[16:17], v[18:19], 0, v[48:49]
	global_load_dwordx4 v[16:19], v[16:17], off
	s_movk_i32 s0, 0x440
	v_lshlrev_b32_e32 v58, 2, v131
	v_mul_lo_u32 v59, v130, s0
	v_add3_u32 v58, s9, v58, v59
	ds_write2_b32 v58, v0, v32 offset1:32
	ds_write2_b32 v58, v1, v33 offset0:68 offset1:100
	ds_write2_b32 v58, v2, v34 offset0:136 offset1:168
	ds_write2_b32 v58, v3, v35 offset0:204 offset1:236
	v_add_u32_e32 v0, 0x800, v58
	ds_write2_b32 v0, v4, v36 offset0:32 offset1:64
	ds_write2_b32 v0, v5, v37 offset0:100 offset1:132
	ds_write2_b32 v0, v6, v38 offset0:168 offset1:200
	v_add_u32_e32 v0, 0xa00, v58
	ds_write2_b32 v0, v7, v39 offset0:108 offset1:140
	v_add_u32_e32 v0, 0x1000, v58
	ds_write2_b32 v0, v8, v40 offset0:64 offset1:96
	ds_write2_b32 v0, v9, v41 offset0:132 offset1:164
	ds_write2_b32 v0, v10, v42 offset0:200 offset1:232
	v_add_u32_e32 v0, 0x1400, v58
	ds_write2_b32 v0, v11, v43 offset0:12 offset1:44
	v_add_u32_e32 v0, 0x1800, v58
	ds_write2_b32 v0, v12, v44 offset0:96 offset1:128
	ds_write2_b32 v0, v13, v45 offset0:164 offset1:196
	v_add_u32_e32 v0, 0x1a00, v58
	ds_write2_b32 v0, v14, v46 offset0:104 offset1:136
	v_add_u32_e32 v0, 0x1c00, v58
	ds_write2_b32 v0, v15, v47 offset0:44 offset1:76
	v_lshlrev_b32_e32 v0, 2, v57
	v_mul_lo_u32 v1, v56, s77
	v_add3_u32 v9, s9, v0, v1
	v_lshl_add_u32 v12, v56, 2, s6
	s_waitcnt lgkmcnt(0)
	ds_read_b128 v[0:3], v9
	ds_read_b128 v[4:7], v9 offset:16
	ds_read_b32 v8, v12
	s_mov_b64 s[40:41], s[42:43]
	s_waitcnt lgkmcnt(0)
	v_pk_mul_f32 v[0:1], v[0:1], v[8:9] op_sel_hi:[1,0]
	v_pk_mul_f32 v[2:3], v[2:3], v[8:9] op_sel_hi:[1,0]
	s_waitcnt vmcnt(0)
	v_lshlrev_b32_e32 v10, 16, v28
	v_and_b32_e32 v11, 0xffff0000, v28
	v_pk_mul_f32 v[0:1], v[0:1], v[10:11]
	v_lshlrev_b32_e32 v10, 16, v29
	v_and_b32_e32 v11, 0xffff0000, v29
	v_pk_mul_f32 v[2:3], v[2:3], v[10:11]
	v_cvt_pk_bf16_f32 v0, v0, v1
	v_cvt_pk_bf16_f32 v1, v2, v3
	v_pk_mul_f32 v[2:3], v[4:5], v[8:9] op_sel_hi:[1,0]
	v_lshlrev_b32_e32 v4, 16, v30
	v_and_b32_e32 v5, 0xffff0000, v30
	v_pk_mul_f32 v[2:3], v[2:3], v[4:5]
	v_pk_mul_f32 v[4:5], v[6:7], v[8:9] op_sel_hi:[1,0]
	v_lshlrev_b32_e32 v6, 16, v31
	v_and_b32_e32 v7, 0xffff0000, v31
	v_pk_mul_f32 v[4:5], v[4:5], v[6:7]
	v_cvt_pk_bf16_f32 v2, v2, v3
	v_cvt_pk_bf16_f32 v3, v4, v5
	v_lshl_add_u64 v[4:5], s[26:27], 0, v[54:55]
	v_lshl_add_u64 v[4:5], v[4:5], 0, s[28:29]
	v_lshl_add_u64 v[4:5], v[4:5], 0, v[80:81]
	v_cmp_eq_u32_e64 s[100:101], 0, v218
	s_nop 3
	s_mov_b64 exec, s[100:101]
	global_atomic_add v221, v[174:175], v181, off sc0
	s_mov_b64 exec, -1
	global_store_dwordx4 v[4:5], v[0:3], off sc1
	s_nop 1
	ds_read_b128 v[0:3], v9 offset:2176
	ds_read_b128 v[4:7], v9 offset:2192
	ds_read_b32 v8, v12 offset:32
	v_lshlrev_b32_e32 v10, 16, v24
	v_and_b32_e32 v11, 0xffff0000, v24
	s_waitcnt lgkmcnt(0)
	v_pk_mul_f32 v[0:1], v[0:1], v[8:9] op_sel_hi:[1,0]
	s_nop 0
	v_pk_mul_f32 v[0:1], v[0:1], v[10:11]
	v_pk_mul_f32 v[2:3], v[2:3], v[8:9] op_sel_hi:[1,0]
	v_lshlrev_b32_e32 v10, 16, v25
	v_and_b32_e32 v11, 0xffff0000, v25
	v_pk_mul_f32 v[2:3], v[2:3], v[10:11]
	v_cvt_pk_bf16_f32 v0, v0, v1
	v_cvt_pk_bf16_f32 v1, v2, v3
	v_pk_mul_f32 v[2:3], v[4:5], v[8:9] op_sel_hi:[1,0]
	v_lshlrev_b32_e32 v4, 16, v26
	v_and_b32_e32 v5, 0xffff0000, v26
	v_pk_mul_f32 v[2:3], v[2:3], v[4:5]
	v_pk_mul_f32 v[4:5], v[6:7], v[8:9] op_sel_hi:[1,0]
	v_lshlrev_b32_e32 v6, 16, v27
	v_and_b32_e32 v7, 0xffff0000, v27
	v_pk_mul_f32 v[4:5], v[4:5], v[6:7]
	v_cvt_pk_bf16_f32 v2, v2, v3
	v_cvt_pk_bf16_f32 v3, v4, v5
	v_lshl_add_u64 v[4:5], s[26:27], 0, v[52:53]
	v_lshl_add_u64 v[4:5], v[4:5], 0, s[28:29]
	v_lshl_add_u64 v[4:5], v[4:5], 0, v[80:81]
	global_store_dwordx4 v[4:5], v[0:3], off sc1
	s_nop 1
	ds_read_b128 v[0:3], v9 offset:4352
	ds_read_b128 v[4:7], v9 offset:4368
	ds_read_b32 v8, v12 offset:64
	v_lshlrev_b32_e32 v10, 16, v20
	v_and_b32_e32 v11, 0xffff0000, v20
	s_waitcnt lgkmcnt(0)
	v_pk_mul_f32 v[0:1], v[0:1], v[8:9] op_sel_hi:[1,0]
	s_nop 0
	v_pk_mul_f32 v[0:1], v[0:1], v[10:11]
	v_pk_mul_f32 v[2:3], v[2:3], v[8:9] op_sel_hi:[1,0]
	v_lshlrev_b32_e32 v10, 16, v21
	v_and_b32_e32 v11, 0xffff0000, v21
	v_pk_mul_f32 v[2:3], v[2:3], v[10:11]
	v_cvt_pk_bf16_f32 v0, v0, v1
	v_cvt_pk_bf16_f32 v1, v2, v3
	v_pk_mul_f32 v[2:3], v[4:5], v[8:9] op_sel_hi:[1,0]
	v_lshlrev_b32_e32 v4, 16, v22
	v_and_b32_e32 v5, 0xffff0000, v22
	v_pk_mul_f32 v[2:3], v[2:3], v[4:5]
	v_pk_mul_f32 v[4:5], v[6:7], v[8:9] op_sel_hi:[1,0]
	v_lshlrev_b32_e32 v6, 16, v23
	v_and_b32_e32 v7, 0xffff0000, v23
	v_pk_mul_f32 v[4:5], v[4:5], v[6:7]
	v_cvt_pk_bf16_f32 v2, v2, v3
	v_cvt_pk_bf16_f32 v3, v4, v5
	v_lshl_add_u64 v[4:5], s[26:27], 0, v[50:51]
	v_lshl_add_u64 v[4:5], v[4:5], 0, s[28:29]
	v_lshl_add_u64 v[4:5], v[4:5], 0, v[80:81]
	global_store_dwordx4 v[4:5], v[0:3], off sc1
	s_nop 1
	ds_read_b128 v[0:3], v9 offset:6528
	ds_read_b128 v[4:7], v9 offset:6544
	ds_read_b32 v8, v12 offset:96
	v_lshlrev_b32_e32 v10, 16, v16
	v_and_b32_e32 v11, 0xffff0000, v16
	s_waitcnt lgkmcnt(0)
	v_pk_mul_f32 v[0:1], v[0:1], v[8:9] op_sel_hi:[1,0]
	s_nop 0
	v_pk_mul_f32 v[0:1], v[0:1], v[10:11]
	v_pk_mul_f32 v[2:3], v[2:3], v[8:9] op_sel_hi:[1,0]
	v_lshlrev_b32_e32 v10, 16, v17
	v_and_b32_e32 v11, 0xffff0000, v17
	v_pk_mul_f32 v[2:3], v[2:3], v[10:11]
	v_cvt_pk_bf16_f32 v0, v0, v1
	v_cvt_pk_bf16_f32 v1, v2, v3
	v_pk_mul_f32 v[2:3], v[4:5], v[8:9] op_sel_hi:[1,0]
	v_lshlrev_b32_e32 v4, 16, v18
	v_and_b32_e32 v5, 0xffff0000, v18
	v_pk_mul_f32 v[2:3], v[2:3], v[4:5]
	v_pk_mul_f32 v[4:5], v[6:7], v[8:9] op_sel_hi:[1,0]
	v_lshlrev_b32_e32 v6, 16, v19
	v_and_b32_e32 v7, 0xffff0000, v19
	v_pk_mul_f32 v[4:5], v[4:5], v[6:7]
	v_cvt_pk_bf16_f32 v2, v2, v3
	v_cvt_pk_bf16_f32 v3, v4, v5
	v_lshl_add_u64 v[4:5], s[26:27], 0, v[48:49]
	v_lshl_add_u64 v[4:5], v[4:5], 0, s[28:29]
	v_lshl_add_u64 v[4:5], v[4:5], 0, v[80:81]
	global_store_dwordx4 v[4:5], v[0:3], off sc1
	s_nop 1
	s_waitcnt vmcnt(0)
	s_barrier
